# v41_attnbody
# speedup vs baseline: 1.0061x; 1.0061x over previous
; __device__ __forceinline__ f32x4 mfma16(bf16x8 a, bf16x8 b, f32x4 c) { return __builtin_amdgcn_mfma_f32_16x16x32_bf16(a, b, c, 0, 0, 0); }
; __device__ __forceinline__ void attn_item(const bf16_t* __restrict__ Q, const bf16_t* __restrict__ Kp, const bf16_t* __restrict__ VT,
;                                           bf16_t* __restrict__ O, int ldo, int nvalid, const float* __restrict__ qn, const float* __restrict__ kn, bf16_t* sm) {
;     ...
;     if (active) {
;       f32x4 s[2][4];
; #pragma unroll
;       for (int g = 0; g < 2; ++g)
; #pragma unroll
;         for (int kt = 0; kt < 4; ++kt) s[g][kt] = f32x4{0.f, 0.f, 0.f, 0.f};
;       {
;         bf16x8 kf[2][4];
; #pragma unroll
;         for (int ks = 0; ks < 4; ++ks) kf[0][ks] = *(const bf16x8*)(sK + (l15) * 136 + ks * 32 + quad * 8);
; #pragma unroll
;         for (int kt = 0; kt < 4; ++kt) {
;           if (kt + 1 < 4) {
; #pragma unroll
;             for (int ks = 0; ks < 4; ++ks) kf[(kt + 1) & 1][ks] = *(const bf16x8*)(sK + ((kt + 1) * 16 + l15) * 136 + ks * 32 + quad * 8);
;           }
;           SCHED();
; #pragma unroll
;           for (int ks = 0; ks < 4; ++ks) {
;             s[0][kt] = mfma16(kf[kt & 1][ks], qf[0][ks], s[0][kt]);
;             s[1][kt] = mfma16(kf[kt & 1][ks], qf[1][ks], s[1][kt]);
;           }
;           SCHED();
;         }
;       }
;       if (k0 + 64 > L) {
; #pragma unroll
;         for (int kt = 0; kt < 4; ++kt)
;           if (k0 + kt * 16 >= L) {
;             s[0][kt] = f32x4{-INFINITY, -INFINITY, -INFINITY, -INFINITY};
;             s[1][kt] = f32x4{-INFINITY, -INFINITY, -INFINITY, -INFINITY};
;           }
;       }
;       bf16x8 pf[2][2];
; #pragma unroll
;       for (int g = 0; g < 2; ++g) {
;         float rs = 0.f;
; #pragma unroll
;         for (int kt = 0; kt < 4; ++kt)
; #pragma unroll
;           for (int j = 0; j < 4; ++j) {
;             float pv = __builtin_amdgcn_exp2f(s[g][kt][j] * cscale - mc);
;             s[g][kt][j] = pv;
;             rs += pv;
;           }
;         l[g] += rs;
; #pragma unroll
;         for (int u = 0; u < 2; ++u) {
;           u32x4 w = {pack2(s[g][2 * u][0], s[g][2 * u][1]), pack2(s[g][2 * u][2], s[g][2 * u][3]),
;                      pack2(s[g][2 * u + 1][0], s[g][2 * u + 1][1]), pack2(s[g][2 * u + 1][2], s[g][2 * u + 1][3])};
;           pf[g][u] = *reinterpret_cast<bf16x8*>(&w);
;         }
;       }
.LBB0_648:
	s_and_saveexec_b64 s[8:9], s[6:7]
	s_cbranch_execz .LBB0_650
	ds_read_b128 v[210:213], v171
	ds_read_b128 v[214:217], v171 offset:64
	ds_read_b128 v[218:221], v171 offset:128
	ds_read_b128 v[222:225], v171 offset:192
	ds_read_b128 v[226:229], v171 offset:4352
	ds_read_b128 v[230:233], v171 offset:4416
	ds_read_b128 v[234:237], v171 offset:4480
	ds_read_b128 v[238:241], v171 offset:4544
	s_waitcnt lgkmcnt(7)
	v_mfma_f32_16x16x32_bf16 v[178:181], v[210:213], v[38:41], 0
	v_mfma_f32_16x16x32_bf16 v[182:185], v[210:213], v[62:65], 0
	s_waitcnt lgkmcnt(6)
	v_mfma_f32_16x16x32_bf16 v[178:181], v[214:217], v[34:37], v[178:181]
	v_mfma_f32_16x16x32_bf16 v[182:185], v[214:217], v[58:61], v[182:185]
	s_waitcnt lgkmcnt(5)
	v_mfma_f32_16x16x32_bf16 v[178:181], v[218:221], v[46:49], v[178:181]
	v_mfma_f32_16x16x32_bf16 v[182:185], v[218:221], v[54:57], v[182:185]
	s_waitcnt lgkmcnt(4)
	v_mfma_f32_16x16x32_bf16 v[178:181], v[222:225], v[42:45], v[178:181]
	v_mfma_f32_16x16x32_bf16 v[182:185], v[222:225], v[50:53], v[182:185]
	ds_read_b128 v[210:213], v171 offset:8704
	ds_read_b128 v[214:217], v171 offset:8768
	ds_read_b128 v[218:221], v171 offset:8832
	ds_read_b128 v[222:225], v171 offset:8896
	s_waitcnt lgkmcnt(7)
	v_mfma_f32_16x16x32_bf16 v[186:189], v[226:229], v[38:41], 0
	v_mfma_f32_16x16x32_bf16 v[190:193], v[226:229], v[62:65], 0
	s_waitcnt lgkmcnt(6)
	v_mfma_f32_16x16x32_bf16 v[186:189], v[230:233], v[34:37], v[186:189]
	v_mfma_f32_16x16x32_bf16 v[190:193], v[230:233], v[58:61], v[190:193]
	s_waitcnt lgkmcnt(5)
	v_mfma_f32_16x16x32_bf16 v[186:189], v[234:237], v[46:49], v[186:189]
	v_mfma_f32_16x16x32_bf16 v[190:193], v[234:237], v[54:57], v[190:193]
	s_waitcnt lgkmcnt(4)
	v_mfma_f32_16x16x32_bf16 v[186:189], v[238:241], v[42:45], v[186:189]
	v_mfma_f32_16x16x32_bf16 v[190:193], v[238:241], v[50:53], v[190:193]
	ds_read_b128 v[226:229], v171 offset:13056
	ds_read_b128 v[230:233], v171 offset:13120
	ds_read_b128 v[234:237], v171 offset:13184
	ds_read_b128 v[238:241], v171 offset:13248
	s_waitcnt lgkmcnt(7)
	v_mfma_f32_16x16x32_bf16 v[194:197], v[210:213], v[38:41], 0
	v_mfma_f32_16x16x32_bf16 v[198:201], v[210:213], v[62:65], 0
	v_fma_f32 v0, v178, s53, -v170
	v_exp_f32_e32 v178, v0
	v_fma_f32 v131, v182, s53, -v170
	v_exp_f32_e32 v182, v131
	s_waitcnt lgkmcnt(6)
	v_mfma_f32_16x16x32_bf16 v[194:197], v[214:217], v[34:37], v[194:197]
	v_mfma_f32_16x16x32_bf16 v[198:201], v[214:217], v[58:61], v[198:201]
	v_fma_f32 v0, v179, s53, -v170
	v_exp_f32_e32 v179, v0
	v_fma_f32 v131, v183, s53, -v170
	v_exp_f32_e32 v183, v131
	v_add_f32_e32 v144, v144, v178
	v_add_f32_e32 v145, v145, v182
	s_waitcnt lgkmcnt(5)
	v_mfma_f32_16x16x32_bf16 v[194:197], v[218:221], v[46:49], v[194:197]
	v_mfma_f32_16x16x32_bf16 v[198:201], v[218:221], v[54:57], v[198:201]
	v_fma_f32 v0, v180, s53, -v170
	v_exp_f32_e32 v180, v0
	v_fma_f32 v131, v184, s53, -v170
	v_exp_f32_e32 v184, v131
	v_add_f32_e32 v144, v144, v179
	v_add_f32_e32 v145, v145, v183
	s_waitcnt lgkmcnt(4)
	v_mfma_f32_16x16x32_bf16 v[194:197], v[222:225], v[42:45], v[194:197]
	v_mfma_f32_16x16x32_bf16 v[198:201], v[222:225], v[50:53], v[198:201]
	v_fma_f32 v0, v181, s53, -v170
	v_exp_f32_e32 v181, v0
	v_fma_f32 v131, v185, s53, -v170
	v_exp_f32_e32 v185, v131
	v_add_f32_e32 v144, v144, v180
	v_add_f32_e32 v145, v145, v184
	v_add_f32_e32 v144, v144, v181
	v_add_f32_e32 v145, v145, v185
	ds_read_b64 v[210:211], v149 offset:34816
	ds_read_b64 v[212:213], v149 offset:34848
	ds_read_b64 v[214:215], v149 offset:37120
	ds_read_b64 v[216:217], v149 offset:37152
	ds_read_b64 v[218:219], v149 offset:39424
	ds_read_b64 v[220:221], v149 offset:39456
	ds_read_b64 v[222:223], v149 offset:41728
	ds_read_b64 v[224:225], v149 offset:41760
	s_waitcnt lgkmcnt(11)
	v_mfma_f32_16x16x32_bf16 v[202:205], v[226:229], v[38:41], 0
	v_mfma_f32_16x16x32_bf16 v[206:209], v[226:229], v[62:65], 0
	v_fma_f32 v0, v186, s53, -v170
	v_exp_f32_e32 v186, v0
	v_fma_f32 v131, v190, s53, -v170
	v_exp_f32_e32 v190, v131
	s_waitcnt lgkmcnt(10)
	v_mfma_f32_16x16x32_bf16 v[202:205], v[230:233], v[34:37], v[202:205]
	v_mfma_f32_16x16x32_bf16 v[206:209], v[230:233], v[58:61], v[206:209]
	v_fma_f32 v0, v187, s53, -v170
	v_exp_f32_e32 v187, v0
	v_fma_f32 v131, v191, s53, -v170
	v_exp_f32_e32 v191, v131
	v_add_f32_e32 v144, v144, v186
	v_add_f32_e32 v145, v145, v190
	s_waitcnt lgkmcnt(9)
	v_mfma_f32_16x16x32_bf16 v[202:205], v[234:237], v[46:49], v[202:205]
	v_mfma_f32_16x16x32_bf16 v[206:209], v[234:237], v[54:57], v[206:209]
	v_fma_f32 v0, v188, s53, -v170
	v_exp_f32_e32 v188, v0
	v_fma_f32 v131, v192, s53, -v170
	v_exp_f32_e32 v192, v131
	v_add_f32_e32 v144, v144, v187
	v_add_f32_e32 v145, v145, v191
	s_waitcnt lgkmcnt(8)
	v_mfma_f32_16x16x32_bf16 v[202:205], v[238:241], v[42:45], v[202:205]
	v_mfma_f32_16x16x32_bf16 v[206:209], v[238:241], v[50:53], v[206:209]
	v_fma_f32 v0, v189, s53, -v170
	v_exp_f32_e32 v189, v0
	v_fma_f32 v131, v193, s53, -v170
	v_exp_f32_e32 v193, v131
	v_add_f32_e32 v144, v144, v188
	v_add_f32_e32 v145, v145, v192
	v_add_f32_e32 v144, v144, v189
	v_add_f32_e32 v145, v145, v193
	ds_read_b64 v[226:227], v149 offset:44032
	ds_read_b64 v[228:229], v149 offset:44064
	ds_read_b64 v[230:231], v149 offset:46336
	ds_read_b64 v[232:233], v149 offset:46368
	ds_read_b64 v[234:235], v149 offset:48640
	ds_read_b64 v[236:237], v149 offset:48672
	ds_read_b64 v[238:239], v149 offset:50944
	ds_read_b64 v[240:241], v149 offset:50976
	v_cvt_pk_bf16_f32 v242, v178, v179
	v_cvt_pk_bf16_f32 v243, v180, v181
	v_cvt_pk_bf16_f32 v244, v186, v187
	v_cvt_pk_bf16_f32 v245, v188, v189
	v_cvt_pk_bf16_f32 v246, v182, v183
	v_cvt_pk_bf16_f32 v247, v184, v185
	v_cvt_pk_bf16_f32 v248, v190, v191
	v_cvt_pk_bf16_f32 v249, v192, v193
	v_fma_f32 v0, v194, s53, -v170
	v_exp_f32_e32 v194, v0
	v_fma_f32 v131, v198, s53, -v170
	v_exp_f32_e32 v198, v131
	s_waitcnt lgkmcnt(14)
; __device__ __forceinline__ f32x4 mfma16(bf16x8 a, bf16x8 b, f32x4 c) { return __builtin_amdgcn_mfma_f32_16x16x32_bf16(a, b, c, 0, 0, 0); }
; #define SCHED() __builtin_amdgcn_sched_barrier(0)
; __device__ __forceinline__ void attn_item(const bf16_t* __restrict__ Q, const bf16_t* __restrict__ Kp, const bf16_t* __restrict__ VT,
;                                           bf16_t* __restrict__ O, int ldo, int nvalid, const float* __restrict__ qn, const float* __restrict__ kn, bf16_t* sm) {
;     ...
;       for (int g = 0; g < 2; ++g) {
;         float rs = 0.f;
; #pragma unroll
;         for (int kt = 0; kt < 4; ++kt)
; #pragma unroll
;           for (int j = 0; j < 4; ++j) {
;             float pv = __builtin_amdgcn_exp2f(s[g][kt][j] * cscale - mc);
;             s[g][kt][j] = pv;
;             rs += pv;
;           }
;         l[g] += rs;
; #pragma unroll
;         for (int u = 0; u < 2; ++u) {
;           u32x4 w = {pack2(s[g][2 * u][0], s[g][2 * u][1]), pack2(s[g][2 * u][2], s[g][2 * u][3]),
;                      pack2(s[g][2 * u + 1][0], s[g][2 * u + 1][1]), pack2(s[g][2 * u + 1][2], s[g][2 * u + 1][3])};
;           pf[g][u] = *reinterpret_cast<bf16x8*>(&w);
;         }
;       }
; #pragma unroll
;       for (int u = 0; u < 2; ++u) {
;         bf16x8 vf[8];
; #pragma unroll
;         for (int dt = 0; dt < 8; ++dt) {
;           u32x2 v0 = *(const u32x2*)(sV + (dt * 16 + l15) * 72 + (2 * u) * 16 + quad * 4);
;           u32x2 v1 = *(const u32x2*)(sV + (dt * 16 + l15) * 72 + (2 * u + 1) * 16 + quad * 4);
;           u32x4 w = {v0.x, v0.y, v1.x, v1.y};
;           vf[dt] = *reinterpret_cast<bf16x8*>(&w);
;         }
;         SCHED();
; #pragma unroll
;         for (int dt = 0; dt < 8; ++dt) {
;           o[0][dt] = mfma16(vf[dt], pf[0][u], o[0][dt]);
;           o[1][dt] = mfma16(vf[dt], pf[1][u], o[1][dt]);
;         }
;         SCHED();
;       }
	v_mfma_f32_16x16x32_bf16 v[94:97], v[210:213], v[242:245], v[94:97]
	v_mfma_f32_16x16x32_bf16 v[30:33], v[210:213], v[246:249], v[30:33]
	v_fma_f32 v0, v195, s53, -v170
	v_exp_f32_e32 v195, v0
	v_fma_f32 v131, v199, s53, -v170
	v_exp_f32_e32 v199, v131
	s_waitcnt lgkmcnt(12)
	v_mfma_f32_16x16x32_bf16 v[90:93], v[214:217], v[242:245], v[90:93]
	v_mfma_f32_16x16x32_bf16 v[26:29], v[214:217], v[246:249], v[26:29]
	v_add_f32_e32 v144, v144, v194
	v_add_f32_e32 v145, v145, v198
	ds_read_b64 v[210:211], v149 offset:34880
	ds_read_b64 v[212:213], v149 offset:34912
	v_fma_f32 v0, v196, s53, -v170
	v_exp_f32_e32 v196, v0
	v_fma_f32 v131, v200, s53, -v170
	v_exp_f32_e32 v200, v131
	s_waitcnt lgkmcnt(12)
	v_mfma_f32_16x16x32_bf16 v[86:89], v[218:221], v[242:245], v[86:89]
	v_mfma_f32_16x16x32_bf16 v[22:25], v[218:221], v[246:249], v[22:25]
	v_add_f32_e32 v144, v144, v195
	v_add_f32_e32 v145, v145, v199
	ds_read_b64 v[214:215], v149 offset:37184
	ds_read_b64 v[216:217], v149 offset:37216
	v_fma_f32 v0, v197, s53, -v170
	v_exp_f32_e32 v197, v0
	v_fma_f32 v131, v201, s53, -v170
	v_exp_f32_e32 v201, v131
	s_waitcnt lgkmcnt(12)
	v_mfma_f32_16x16x32_bf16 v[82:85], v[222:225], v[242:245], v[82:85]
	v_mfma_f32_16x16x32_bf16 v[18:21], v[222:225], v[246:249], v[18:21]
	v_add_f32_e32 v144, v144, v196
	v_add_f32_e32 v145, v145, v200
	ds_read_b64 v[218:219], v149 offset:39488
	ds_read_b64 v[220:221], v149 offset:39520
	v_fma_f32 v0, v202, s53, -v170
	v_exp_f32_e32 v202, v0
	v_fma_f32 v131, v206, s53, -v170
	v_exp_f32_e32 v206, v131
	s_waitcnt lgkmcnt(12)
	v_mfma_f32_16x16x32_bf16 v[78:81], v[226:229], v[242:245], v[78:81]
	v_mfma_f32_16x16x32_bf16 v[14:17], v[226:229], v[246:249], v[14:17]
	v_add_f32_e32 v144, v144, v197
	v_add_f32_e32 v145, v145, v201
	ds_read_b64 v[222:223], v149 offset:41792
	ds_read_b64 v[224:225], v149 offset:41824
	v_fma_f32 v0, v203, s53, -v170
	v_exp_f32_e32 v203, v0
	v_fma_f32 v131, v207, s53, -v170
	v_exp_f32_e32 v207, v131
	s_waitcnt lgkmcnt(12)
	v_mfma_f32_16x16x32_bf16 v[74:77], v[230:233], v[242:245], v[74:77]
	v_mfma_f32_16x16x32_bf16 v[10:13], v[230:233], v[246:249], v[10:13]
	v_add_f32_e32 v144, v144, v202
	v_add_f32_e32 v145, v145, v206
	ds_read_b64 v[226:227], v149 offset:44096
	ds_read_b64 v[228:229], v149 offset:44128
	v_fma_f32 v0, v204, s53, -v170
	v_exp_f32_e32 v204, v0
	v_fma_f32 v131, v208, s53, -v170
	v_exp_f32_e32 v208, v131
	s_waitcnt lgkmcnt(12)
	v_mfma_f32_16x16x32_bf16 v[70:73], v[234:237], v[242:245], v[70:73]
	v_mfma_f32_16x16x32_bf16 v[6:9], v[234:237], v[246:249], v[6:9]
	v_add_f32_e32 v144, v144, v203
	v_add_f32_e32 v145, v145, v207
	ds_read_b64 v[230:231], v149 offset:46400
	ds_read_b64 v[232:233], v149 offset:46432
	v_fma_f32 v0, v205, s53, -v170
	v_exp_f32_e32 v205, v0
	v_fma_f32 v131, v209, s53, -v170
	v_exp_f32_e32 v209, v131
	s_waitcnt lgkmcnt(12)
	v_mfma_f32_16x16x32_bf16 v[66:69], v[238:241], v[242:245], v[66:69]
	v_mfma_f32_16x16x32_bf16 v[2:5], v[238:241], v[246:249], v[2:5]
	v_add_f32_e32 v144, v144, v204
	v_add_f32_e32 v145, v145, v208
	ds_read_b64 v[234:235], v149 offset:48704
	ds_read_b64 v[236:237], v149 offset:48736
	v_add_f32_e32 v144, v144, v205
	v_add_f32_e32 v145, v145, v209
	ds_read_b64 v[238:239], v149 offset:51008
	ds_read_b64 v[240:241], v149 offset:51040
	v_cvt_pk_bf16_f32 v178, v194, v195
	v_cvt_pk_bf16_f32 v179, v196, v197
	v_cvt_pk_bf16_f32 v180, v202, v203
	v_cvt_pk_bf16_f32 v181, v204, v205
	v_cvt_pk_bf16_f32 v182, v198, v199
	v_cvt_pk_bf16_f32 v183, v200, v201
	v_cvt_pk_bf16_f32 v184, v206, v207
	v_cvt_pk_bf16_f32 v185, v208, v209
	s_nop 3
	s_waitcnt lgkmcnt(14)
	v_mfma_f32_16x16x32_bf16 v[94:97], v[210:213], v[178:181], v[94:97]
	v_mfma_f32_16x16x32_bf16 v[30:33], v[210:213], v[182:185], v[30:33]
	s_waitcnt lgkmcnt(12)
	v_mfma_f32_16x16x32_bf16 v[90:93], v[214:217], v[178:181], v[90:93]
	v_mfma_f32_16x16x32_bf16 v[26:29], v[214:217], v[182:185], v[26:29]
	s_waitcnt lgkmcnt(10)
	v_mfma_f32_16x16x32_bf16 v[86:89], v[218:221], v[178:181], v[86:89]
	v_mfma_f32_16x16x32_bf16 v[22:25], v[218:221], v[182:185], v[22:25]
	s_waitcnt lgkmcnt(8)
	v_mfma_f32_16x16x32_bf16 v[82:85], v[222:225], v[178:181], v[82:85]
	v_mfma_f32_16x16x32_bf16 v[18:21], v[222:225], v[182:185], v[18:21]
	s_waitcnt lgkmcnt(6)
	v_mfma_f32_16x16x32_bf16 v[78:81], v[226:229], v[178:181], v[78:81]
	v_mfma_f32_16x16x32_bf16 v[14:17], v[226:229], v[182:185], v[14:17]
	s_waitcnt lgkmcnt(4)
	v_mfma_f32_16x16x32_bf16 v[74:77], v[230:233], v[178:181], v[74:77]
	v_mfma_f32_16x16x32_bf16 v[10:13], v[230:233], v[182:185], v[10:13]
	s_waitcnt lgkmcnt(2)
	v_mfma_f32_16x16x32_bf16 v[70:73], v[234:237], v[178:181], v[70:73]
	v_mfma_f32_16x16x32_bf16 v[6:9], v[234:237], v[182:185], v[6:9]
	s_waitcnt lgkmcnt(0)
	v_mfma_f32_16x16x32_bf16 v[66:69], v[238:241], v[178:181], v[66:69]
	v_mfma_f32_16x16x32_bf16 v[2:5], v[238:241], v[182:185], v[2:5]

; __device__ __forceinline__ f32x4 mfma16(bf16x8 a, bf16x8 b, f32x4 c) { return __builtin_amdgcn_mfma_f32_16x16x32_bf16(a, b, c, 0, 0, 0); }
; __device__ __forceinline__ void attn_item(const bf16_t* __restrict__ Q, const bf16_t* __restrict__ Kp, const bf16_t* __restrict__ VT,
;                                           bf16_t* __restrict__ O, int ldo, int nvalid, const float* __restrict__ qn, const float* __restrict__ kn, bf16_t* sm) {
;     ...
;     if (active) {
;       f32x4 s[2][4];
; #pragma unroll
;       for (int g = 0; g < 2; ++g)
; #pragma unroll
;         for (int kt = 0; kt < 4; ++kt) s[g][kt] = f32x4{0.f, 0.f, 0.f, 0.f};
;       {
;         bf16x8 kf[2][4];
; #pragma unroll
;         for (int ks = 0; ks < 4; ++ks) kf[0][ks] = *(const bf16x8*)(sK + (l15) * 136 + ks * 32 + quad * 8);
; #pragma unroll
;         for (int kt = 0; kt < 4; ++kt) {
;           if (kt + 1 < 4) {
; #pragma unroll
;             for (int ks = 0; ks < 4; ++ks) kf[(kt + 1) & 1][ks] = *(const bf16x8*)(sK + ((kt + 1) * 16 + l15) * 136 + ks * 32 + quad * 8);
;           }
;           SCHED();
; #pragma unroll
;           for (int ks = 0; ks < 4; ++ks) {
;             s[0][kt] = mfma16(kf[kt & 1][ks], qf[0][ks], s[0][kt]);
;             s[1][kt] = mfma16(kf[kt & 1][ks], qf[1][ks], s[1][kt]);
;           }
;           SCHED();
;         }
;       }
;       if (k0 + 64 > L) {
; #pragma unroll
;         for (int kt = 0; kt < 4; ++kt)
;           if (k0 + kt * 16 >= L) {
;             s[0][kt] = f32x4{-INFINITY, -INFINITY, -INFINITY, -INFINITY};
;             s[1][kt] = f32x4{-INFINITY, -INFINITY, -INFINITY, -INFINITY};
;           }
;       }
;       bf16x8 pf[2][2];
; #pragma unroll
;       for (int g = 0; g < 2; ++g) {
;         float rs = 0.f;
; #pragma unroll
;         for (int kt = 0; kt < 4; ++kt)
; #pragma unroll
;           for (int j = 0; j < 4; ++j) {
;             float pv = __builtin_amdgcn_exp2f(s[g][kt][j] * cscale - mc);
;             s[g][kt][j] = pv;
;             rs += pv;
;           }
;         l[g] += rs;
; #pragma unroll
;         for (int u = 0; u < 2; ++u) {
;           u32x4 w = {pack2(s[g][2 * u][0], s[g][2 * u][1]), pack2(s[g][2 * u][2], s[g][2 * u][3]),
;                      pack2(s[g][2 * u + 1][0], s[g][2 * u + 1][1]), pack2(s[g][2 * u + 1][2], s[g][2 * u + 1][3])};
;           pf[g][u] = *reinterpret_cast<bf16x8*>(&w);
;         }
;       }
.LBB0_652:
	s_and_saveexec_b64 s[8:9], s[6:7]
	s_cbranch_execz .LBB0_645
	ds_read_b128 v[210:213], v171 offset:17408
	ds_read_b128 v[214:217], v171 offset:17472
	ds_read_b128 v[218:221], v171 offset:17536
	ds_read_b128 v[222:225], v171 offset:17600
	ds_read_b128 v[226:229], v171 offset:21760
	ds_read_b128 v[230:233], v171 offset:21824
	ds_read_b128 v[234:237], v171 offset:21888
	ds_read_b128 v[238:241], v171 offset:21952
	s_waitcnt lgkmcnt(7)
	v_mfma_f32_16x16x32_bf16 v[178:181], v[210:213], v[38:41], 0
	v_mfma_f32_16x16x32_bf16 v[182:185], v[210:213], v[62:65], 0
	s_waitcnt lgkmcnt(6)
	v_mfma_f32_16x16x32_bf16 v[178:181], v[214:217], v[34:37], v[178:181]
	v_mfma_f32_16x16x32_bf16 v[182:185], v[214:217], v[58:61], v[182:185]
	s_waitcnt lgkmcnt(5)
	v_mfma_f32_16x16x32_bf16 v[178:181], v[218:221], v[46:49], v[178:181]
	v_mfma_f32_16x16x32_bf16 v[182:185], v[218:221], v[54:57], v[182:185]
	s_waitcnt lgkmcnt(4)
	v_mfma_f32_16x16x32_bf16 v[178:181], v[222:225], v[42:45], v[178:181]
	v_mfma_f32_16x16x32_bf16 v[182:185], v[222:225], v[50:53], v[182:185]
	ds_read_b128 v[210:213], v171 offset:26112
	ds_read_b128 v[214:217], v171 offset:26176
	ds_read_b128 v[218:221], v171 offset:26240
	ds_read_b128 v[222:225], v171 offset:26304
	s_waitcnt lgkmcnt(7)
	v_mfma_f32_16x16x32_bf16 v[186:189], v[226:229], v[38:41], 0
	v_mfma_f32_16x16x32_bf16 v[190:193], v[226:229], v[62:65], 0
	s_waitcnt lgkmcnt(6)
	v_mfma_f32_16x16x32_bf16 v[186:189], v[230:233], v[34:37], v[186:189]
	v_mfma_f32_16x16x32_bf16 v[190:193], v[230:233], v[58:61], v[190:193]
	s_waitcnt lgkmcnt(5)
	v_mfma_f32_16x16x32_bf16 v[186:189], v[234:237], v[46:49], v[186:189]
	v_mfma_f32_16x16x32_bf16 v[190:193], v[234:237], v[54:57], v[190:193]
	s_waitcnt lgkmcnt(4)
	v_mfma_f32_16x16x32_bf16 v[186:189], v[238:241], v[42:45], v[186:189]
	v_mfma_f32_16x16x32_bf16 v[190:193], v[238:241], v[50:53], v[190:193]
	ds_read_b128 v[226:229], v171 offset:30464
	ds_read_b128 v[230:233], v171 offset:30528
	ds_read_b128 v[234:237], v171 offset:30592
	ds_read_b128 v[238:241], v171 offset:30656
	s_waitcnt lgkmcnt(7)
	v_mfma_f32_16x16x32_bf16 v[194:197], v[210:213], v[38:41], 0
	v_mfma_f32_16x16x32_bf16 v[198:201], v[210:213], v[62:65], 0
	v_fma_f32 v0, v178, s53, -v170
	v_exp_f32_e32 v178, v0
	v_fma_f32 v131, v182, s53, -v170
	v_exp_f32_e32 v182, v131
	s_waitcnt lgkmcnt(6)
	v_mfma_f32_16x16x32_bf16 v[194:197], v[214:217], v[34:37], v[194:197]
	v_mfma_f32_16x16x32_bf16 v[198:201], v[214:217], v[58:61], v[198:201]
	v_fma_f32 v0, v179, s53, -v170
	v_exp_f32_e32 v179, v0
	v_fma_f32 v131, v183, s53, -v170
	v_exp_f32_e32 v183, v131
	v_add_f32_e32 v144, v144, v178
	v_add_f32_e32 v145, v145, v182
	s_waitcnt lgkmcnt(5)
	v_mfma_f32_16x16x32_bf16 v[194:197], v[218:221], v[46:49], v[194:197]
	v_mfma_f32_16x16x32_bf16 v[198:201], v[218:221], v[54:57], v[198:201]
	v_fma_f32 v0, v180, s53, -v170
	v_exp_f32_e32 v180, v0
	v_fma_f32 v131, v184, s53, -v170
	v_exp_f32_e32 v184, v131
	v_add_f32_e32 v144, v144, v179
	v_add_f32_e32 v145, v145, v183
	s_waitcnt lgkmcnt(4)
	v_mfma_f32_16x16x32_bf16 v[194:197], v[222:225], v[42:45], v[194:197]
	v_mfma_f32_16x16x32_bf16 v[198:201], v[222:225], v[50:53], v[198:201]
	v_fma_f32 v0, v181, s53, -v170
	v_exp_f32_e32 v181, v0
	v_fma_f32 v131, v185, s53, -v170
	v_exp_f32_e32 v185, v131
	v_add_f32_e32 v144, v144, v180
	v_add_f32_e32 v145, v145, v184
	v_add_f32_e32 v144, v144, v181
	v_add_f32_e32 v145, v145, v185
	ds_read_b64 v[210:211], v172
	ds_read_b64 v[212:213], v172 offset:32
	ds_read_b64 v[214:215], v172 offset:2304
	ds_read_b64 v[216:217], v172 offset:2336
	ds_read_b64 v[218:219], v172 offset:4608
	ds_read_b64 v[220:221], v172 offset:4640
	ds_read_b64 v[222:223], v172 offset:6912
	ds_read_b64 v[224:225], v172 offset:6944
	s_waitcnt lgkmcnt(11)
	v_mfma_f32_16x16x32_bf16 v[202:205], v[226:229], v[38:41], 0
	v_mfma_f32_16x16x32_bf16 v[206:209], v[226:229], v[62:65], 0
	v_fma_f32 v0, v186, s53, -v170
	v_exp_f32_e32 v186, v0
	v_fma_f32 v131, v190, s53, -v170
	v_exp_f32_e32 v190, v131
	s_waitcnt lgkmcnt(10)
	v_mfma_f32_16x16x32_bf16 v[202:205], v[230:233], v[34:37], v[202:205]
	v_mfma_f32_16x16x32_bf16 v[206:209], v[230:233], v[58:61], v[206:209]
	v_fma_f32 v0, v187, s53, -v170
	v_exp_f32_e32 v187, v0
	v_fma_f32 v131, v191, s53, -v170
	v_exp_f32_e32 v191, v131
	v_add_f32_e32 v144, v144, v186
	v_add_f32_e32 v145, v145, v190
	s_waitcnt lgkmcnt(9)
	v_mfma_f32_16x16x32_bf16 v[202:205], v[234:237], v[46:49], v[202:205]
	v_mfma_f32_16x16x32_bf16 v[206:209], v[234:237], v[54:57], v[206:209]
	v_fma_f32 v0, v188, s53, -v170
	v_exp_f32_e32 v188, v0
	v_fma_f32 v131, v192, s53, -v170
	v_exp_f32_e32 v192, v131
	v_add_f32_e32 v144, v144, v187
	v_add_f32_e32 v145, v145, v191
	s_waitcnt lgkmcnt(8)
	v_mfma_f32_16x16x32_bf16 v[202:205], v[238:241], v[42:45], v[202:205]
	v_mfma_f32_16x16x32_bf16 v[206:209], v[238:241], v[50:53], v[206:209]
	v_fma_f32 v0, v189, s53, -v170
	v_exp_f32_e32 v189, v0
	v_fma_f32 v131, v193, s53, -v170
	v_exp_f32_e32 v193, v131
	v_add_f32_e32 v144, v144, v188
	v_add_f32_e32 v145, v145, v192
	v_add_f32_e32 v144, v144, v189
	v_add_f32_e32 v145, v145, v193
	ds_read_b64 v[226:227], v172 offset:9216
	ds_read_b64 v[228:229], v172 offset:9248
	ds_read_b64 v[230:231], v172 offset:11520
	ds_read_b64 v[232:233], v172 offset:11552
	ds_read_b64 v[234:235], v172 offset:13824
	ds_read_b64 v[236:237], v172 offset:13856
	ds_read_b64 v[238:239], v172 offset:16128
	ds_read_b64 v[240:241], v172 offset:16160
	v_cvt_pk_bf16_f32 v242, v178, v179
	v_cvt_pk_bf16_f32 v243, v180, v181
	v_cvt_pk_bf16_f32 v244, v186, v187
	v_cvt_pk_bf16_f32 v245, v188, v189
	v_cvt_pk_bf16_f32 v246, v182, v183
	v_cvt_pk_bf16_f32 v247, v184, v185
	v_cvt_pk_bf16_f32 v248, v190, v191
	v_cvt_pk_bf16_f32 v249, v192, v193
	v_fma_f32 v0, v194, s53, -v170
	v_exp_f32_e32 v194, v0
	v_fma_f32 v131, v198, s53, -v170
	v_exp_f32_e32 v198, v131
	s_waitcnt lgkmcnt(14)
; __device__ __forceinline__ f32x4 mfma16(bf16x8 a, bf16x8 b, f32x4 c) { return __builtin_amdgcn_mfma_f32_16x16x32_bf16(a, b, c, 0, 0, 0); }
; #define SCHED() __builtin_amdgcn_sched_barrier(0)
; __device__ __forceinline__ void attn_item(const bf16_t* __restrict__ Q, const bf16_t* __restrict__ Kp, const bf16_t* __restrict__ VT,
;                                           bf16_t* __restrict__ O, int ldo, int nvalid, const float* __restrict__ qn, const float* __restrict__ kn, bf16_t* sm) {
;     ...
;       for (int g = 0; g < 2; ++g) {
;         float rs = 0.f;
; #pragma unroll
;         for (int kt = 0; kt < 4; ++kt)
; #pragma unroll
;           for (int j = 0; j < 4; ++j) {
;             float pv = __builtin_amdgcn_exp2f(s[g][kt][j] * cscale - mc);
;             s[g][kt][j] = pv;
;             rs += pv;
;           }
;         l[g] += rs;
; #pragma unroll
;         for (int u = 0; u < 2; ++u) {
;           u32x4 w = {pack2(s[g][2 * u][0], s[g][2 * u][1]), pack2(s[g][2 * u][2], s[g][2 * u][3]),
;                      pack2(s[g][2 * u + 1][0], s[g][2 * u + 1][1]), pack2(s[g][2 * u + 1][2], s[g][2 * u + 1][3])};
;           pf[g][u] = *reinterpret_cast<bf16x8*>(&w);
;         }
;       }
; #pragma unroll
;       for (int u = 0; u < 2; ++u) {
;         bf16x8 vf[8];
; #pragma unroll
;         for (int dt = 0; dt < 8; ++dt) {
;           u32x2 v0 = *(const u32x2*)(sV + (dt * 16 + l15) * 72 + (2 * u) * 16 + quad * 4);
;           u32x2 v1 = *(const u32x2*)(sV + (dt * 16 + l15) * 72 + (2 * u + 1) * 16 + quad * 4);
;           u32x4 w = {v0.x, v0.y, v1.x, v1.y};
;           vf[dt] = *reinterpret_cast<bf16x8*>(&w);
;         }
;         SCHED();
; #pragma unroll
;         for (int dt = 0; dt < 8; ++dt) {
;           o[0][dt] = mfma16(vf[dt], pf[0][u], o[0][dt]);
;           o[1][dt] = mfma16(vf[dt], pf[1][u], o[1][dt]);
;         }
;         SCHED();
;       }
	v_mfma_f32_16x16x32_bf16 v[94:97], v[210:213], v[242:245], v[94:97]
	v_mfma_f32_16x16x32_bf16 v[30:33], v[210:213], v[246:249], v[30:33]
	v_fma_f32 v0, v195, s53, -v170
	v_exp_f32_e32 v195, v0
	v_fma_f32 v131, v199, s53, -v170
	v_exp_f32_e32 v199, v131
	s_waitcnt lgkmcnt(12)
	v_mfma_f32_16x16x32_bf16 v[90:93], v[214:217], v[242:245], v[90:93]
	v_mfma_f32_16x16x32_bf16 v[26:29], v[214:217], v[246:249], v[26:29]
	v_add_f32_e32 v144, v144, v194
	v_add_f32_e32 v145, v145, v198
	ds_read_b64 v[210:211], v172 offset:64
	ds_read_b64 v[212:213], v172 offset:96
	v_fma_f32 v0, v196, s53, -v170
	v_exp_f32_e32 v196, v0
	v_fma_f32 v131, v200, s53, -v170
	v_exp_f32_e32 v200, v131
	s_waitcnt lgkmcnt(12)
	v_mfma_f32_16x16x32_bf16 v[86:89], v[218:221], v[242:245], v[86:89]
	v_mfma_f32_16x16x32_bf16 v[22:25], v[218:221], v[246:249], v[22:25]
	v_add_f32_e32 v144, v144, v195
	v_add_f32_e32 v145, v145, v199
	ds_read_b64 v[214:215], v172 offset:2368
	ds_read_b64 v[216:217], v172 offset:2400
	v_fma_f32 v0, v197, s53, -v170
	v_exp_f32_e32 v197, v0
	v_fma_f32 v131, v201, s53, -v170
	v_exp_f32_e32 v201, v131
	s_waitcnt lgkmcnt(12)
	v_mfma_f32_16x16x32_bf16 v[82:85], v[222:225], v[242:245], v[82:85]
	v_mfma_f32_16x16x32_bf16 v[18:21], v[222:225], v[246:249], v[18:21]
	v_add_f32_e32 v144, v144, v196
	v_add_f32_e32 v145, v145, v200
	ds_read_b64 v[218:219], v172 offset:4672
	ds_read_b64 v[220:221], v172 offset:4704
	v_fma_f32 v0, v202, s53, -v170
	v_exp_f32_e32 v202, v0
	v_fma_f32 v131, v206, s53, -v170
	v_exp_f32_e32 v206, v131
	s_waitcnt lgkmcnt(12)
	v_mfma_f32_16x16x32_bf16 v[78:81], v[226:229], v[242:245], v[78:81]
	v_mfma_f32_16x16x32_bf16 v[14:17], v[226:229], v[246:249], v[14:17]
	v_add_f32_e32 v144, v144, v197
	v_add_f32_e32 v145, v145, v201
	ds_read_b64 v[222:223], v172 offset:6976
	ds_read_b64 v[224:225], v172 offset:7008
	v_fma_f32 v0, v203, s53, -v170
	v_exp_f32_e32 v203, v0
	v_fma_f32 v131, v207, s53, -v170
	v_exp_f32_e32 v207, v131
	s_waitcnt lgkmcnt(12)
	v_mfma_f32_16x16x32_bf16 v[74:77], v[230:233], v[242:245], v[74:77]
	v_mfma_f32_16x16x32_bf16 v[10:13], v[230:233], v[246:249], v[10:13]
	v_add_f32_e32 v144, v144, v202
	v_add_f32_e32 v145, v145, v206
	ds_read_b64 v[226:227], v172 offset:9280
	ds_read_b64 v[228:229], v172 offset:9312
	v_fma_f32 v0, v204, s53, -v170
	v_exp_f32_e32 v204, v0
	v_fma_f32 v131, v208, s53, -v170
	v_exp_f32_e32 v208, v131
	s_waitcnt lgkmcnt(12)
	v_mfma_f32_16x16x32_bf16 v[70:73], v[234:237], v[242:245], v[70:73]
	v_mfma_f32_16x16x32_bf16 v[6:9], v[234:237], v[246:249], v[6:9]
	v_add_f32_e32 v144, v144, v203
	v_add_f32_e32 v145, v145, v207
	ds_read_b64 v[230:231], v172 offset:11584
	ds_read_b64 v[232:233], v172 offset:11616
	v_fma_f32 v0, v205, s53, -v170
	v_exp_f32_e32 v205, v0
	v_fma_f32 v131, v209, s53, -v170
	v_exp_f32_e32 v209, v131
	s_waitcnt lgkmcnt(12)
	v_mfma_f32_16x16x32_bf16 v[66:69], v[238:241], v[242:245], v[66:69]
	v_mfma_f32_16x16x32_bf16 v[2:5], v[238:241], v[246:249], v[2:5]
	v_add_f32_e32 v144, v144, v204
	v_add_f32_e32 v145, v145, v208
	ds_read_b64 v[234:235], v172 offset:13888
	ds_read_b64 v[236:237], v172 offset:13920
	v_add_f32_e32 v144, v144, v205
	v_add_f32_e32 v145, v145, v209
	ds_read_b64 v[238:239], v172 offset:16192
	ds_read_b64 v[240:241], v172 offset:16224
	v_cvt_pk_bf16_f32 v178, v194, v195
	v_cvt_pk_bf16_f32 v179, v196, v197
	v_cvt_pk_bf16_f32 v180, v202, v203
	v_cvt_pk_bf16_f32 v181, v204, v205
	v_cvt_pk_bf16_f32 v182, v198, v199
	v_cvt_pk_bf16_f32 v183, v200, v201
	v_cvt_pk_bf16_f32 v184, v206, v207
	v_cvt_pk_bf16_f32 v185, v208, v209
	s_nop 3
	s_waitcnt lgkmcnt(14)
	v_mfma_f32_16x16x32_bf16 v[94:97], v[210:213], v[178:181], v[94:97]
	v_mfma_f32_16x16x32_bf16 v[30:33], v[210:213], v[182:185], v[30:33]
	s_waitcnt lgkmcnt(12)
	v_mfma_f32_16x16x32_bf16 v[90:93], v[214:217], v[178:181], v[90:93]
	v_mfma_f32_16x16x32_bf16 v[26:29], v[214:217], v[182:185], v[26:29]
	s_waitcnt lgkmcnt(10)
	v_mfma_f32_16x16x32_bf16 v[86:89], v[218:221], v[178:181], v[86:89]
	v_mfma_f32_16x16x32_bf16 v[22:25], v[218:221], v[182:185], v[22:25]
	s_waitcnt lgkmcnt(8)
	v_mfma_f32_16x16x32_bf16 v[82:85], v[222:225], v[178:181], v[82:85]
	v_mfma_f32_16x16x32_bf16 v[18:21], v[222:225], v[182:185], v[18:21]
	s_waitcnt lgkmcnt(6)
	v_mfma_f32_16x16x32_bf16 v[78:81], v[226:229], v[178:181], v[78:81]
	v_mfma_f32_16x16x32_bf16 v[14:17], v[226:229], v[182:185], v[14:17]
	s_waitcnt lgkmcnt(4)
	v_mfma_f32_16x16x32_bf16 v[74:77], v[230:233], v[178:181], v[74:77]
	v_mfma_f32_16x16x32_bf16 v[10:13], v[230:233], v[182:185], v[10:13]
	s_waitcnt lgkmcnt(2)
	v_mfma_f32_16x16x32_bf16 v[70:73], v[234:237], v[178:181], v[70:73]
	v_mfma_f32_16x16x32_bf16 v[6:9], v[234:237], v[182:185], v[6:9]
	s_waitcnt lgkmcnt(0)
	v_mfma_f32_16x16x32_bf16 v[66:69], v[238:241], v[178:181], v[66:69]
	v_mfma_f32_16x16x32_bf16 v[2:5], v[238:241], v[182:185], v[2:5]
	s_branch .LBB0_645
